# scan loop: per-chunk workgroup barrier replaced by per-wave LDS progress counters between loader and compute waves
# speedup vs baseline: 1.0077x; 1.0077x over previous
.LBB0_493:
	s_or_b64 exec, exec, s[6:7]
	v_mov_b32_e32 v17, 0
	v_and_b32_e32 v18, 15, v0
	v_lshlrev_b32_e32 v23, 2, v1
	s_movk_i32 s14, 0x50
	s_waitcnt vmcnt(0)
	v_add_u32_e32 v16, 0xfffffe80, v0
	v_lshrrev_b32_e32 v0, 2, v3
	v_mov_b32_e32 v1, v17
	v_mad_u32_u24 v24, v18, s14, 0
	v_and_b32_e32 v29, 1, v16
	v_xor_b32_e32 v29, 1, v29
	v_lshrrev_b32_e32 v25, 1, v16
	v_lshl_add_u32 v25, v29, 4, v25
	v_lshlrev_b32_e32 v25, 2, v25
	v_add_u32_e32 v25, 0x8c0, v25
	v_lshlrev_b32_e32 v26, 2, v0
	s_lshl_b64 s[14:15], s[10:11], 21
	v_lshlrev_b64 v[0:1], 9, v[0:1]
	v_and_b32_e32 v27, 12, v2
	v_lshl_add_u64 v[0:1], s[14:15], 0, v[0:1]
	s_and_b32 s33, s72, 3
	v_lshlrev_b32_e32 v2, 1, v2
	v_lshl_or_b32 v0, s36, 7, v0
	s_lshl_b32 s33, s33, 5
	v_and_b32_e32 v2, 24, v2
	v_or3_b32 v0, v0, s33, v2
	v_lshl_add_u64 v[0:1], s[30:31], 0, v[0:1]
	s_mov_b64 s[34:35], 0x1d04000
	v_lshl_add_u64 v[0:1], v[0:1], 0, s[34:35]
	s_lshl_b64 s[34:35], s[10:11], 16
	s_lshl_b32 s33, s36, 2
	s_add_u32 s33, s30, s33
	s_addc_u32 s40, s31, 0
	s_add_u32 s34, s33, s34
	v_and_b32_e32 v22, 3, v6
	s_addc_u32 s35, s40, s35
	s_lshl_b64 s[10:11], s[10:11], 22
	v_lshlrev_b64 v[4:5], 10, v[6:7]
	v_lshlrev_b64 v[12:13], 2, v[8:9]
	v_lshlrev_b64 v[6:7], 9, v[6:7]
	v_lshlrev_b64 v[14:15], 1, v[8:9]
	v_lshlrev_b64 v[8:9], 10, v[10:11]
	v_lshlrev_b64 v[10:11], 9, v[10:11]
	v_and_b32_e32 v19, 12, v23
	v_lshl_add_u64 v[4:5], s[10:11], 0, v[4:5]
	v_lshl_add_u64 v[6:7], s[14:15], 0, v[6:7]
	v_lshl_add_u64 v[8:9], s[10:11], 0, v[8:9]
	v_lshl_add_u64 v[10:11], s[14:15], 0, v[10:11]
	s_movk_i32 s6, 0x7f
	s_movk_i32 s8, 0xa0
	v_lshl_add_u64 v[4:5], v[4:5], 0, v[12:13]
	v_lshl_add_u64 v[6:7], v[6:7], 0, v[14:15]
	v_lshl_add_u64 v[8:9], v[8:9], 0, v[12:13]
	v_lshl_add_u64 v[10:11], v[10:11], 0, v[14:15]
	v_lshl_or_b32 v12, v18, 10, s10
	v_add_u32_e32 v14, s37, v19
	v_cmp_lt_u32_e64 s[6:7], s6, v3
	v_cmp_gt_u32_e64 s[8:9], s8, v3
	v_lshl_add_u64 v[2:3], v[16:17], 4, s[34:35]
	s_mov_b64 s[34:35], 0x780200
	v_lshl_or_b32 v12, s36, 8, v12
	v_mov_b32_e32 v13, s11
	v_add_lshl_u32 v16, v14, v22, 2
	v_lshl_add_u64 v[2:3], v[2:3], 0, s[34:35]
	v_lshl_add_u64 v[4:5], s[30:31], 0, v[4:5]
	s_mov_b64 s[34:35], 0xc508000
	v_lshl_add_u64 v[8:9], s[30:31], 0, v[8:9]
	v_lshl_add_u64 v[12:13], v[12:13], 0, v[16:17]
	v_mov_b32_e32 v16, v17
	v_lshl_add_u64 v[4:5], v[4:5], 0, s[34:35]
	v_lshl_add_u64 v[6:7], s[30:31], 0, v[6:7]
	v_lshl_add_u64 v[8:9], v[8:9], 0, s[34:35]
	v_lshl_add_u64 v[10:11], s[30:31], 0, v[10:11]
	v_lshl_add_u64 v[12:13], s[30:31], 0, v[12:13]
	s_mov_b32 s58, 0
	s_mov_b32 s10, 0xaaaaaaaa
	s_mov_b32 s14, 0xcccccccc
	s_mov_b32 s34, 0xf000f
	s_mov_b32 s36, 0xf000f0
	s_mov_b32 s42, 0xf000f00
	s_mov_b32 s44, 0xf000f000
	s_mov_b32 s59, 0x4d00000
	s_mov_b32 s60, 0xd504000
	s_mov_b32 s61, 0xdd04000
	s_mov_b32 s62, 0xe504000
	s_mov_b32 s63, 0xed04000
	v_mul_u32_u24_e32 v27, 0x90, v27
	s_mov_b64 s[46:47], 0x4000
	s_mov_b64 s[48:49], 0x200
	s_mov_b64 s[50:51], 0x8000
	v_mov_b64_e32 v[18:19], v[16:17]
	v_mov_b32_e32 v28, v17
	v_mov_b32_e32 v60, 0x1f000
	v_mov_b32_e32 v64, 0
	v_mov_b32_e32 v65, 0
	v_mov_b32_e32 v66, 0
	v_mov_b32_e32 v67, 0
	ds_write_b128 v60, v[64:67]
	ds_write_b128 v60, v[64:67] offset:16
	s_waitcnt lgkmcnt(0)
	s_barrier
	s_branch .LBB0_496
.LBB0_494:
	s_or_b64 exec, exec, s[54:55]
	s_waitcnt lgkmcnt(0)
	v_lshrrev_b32_e32 v57, 4, v152
	v_and_b32_e32 v57, 28, v57
	v_add_u32_e32 v57, 0x1eff0, v57
	v_mov_b32_e32 v58, 1
	s_mov_b64 exec, 1
	ds_add_u32 v57, v58
	s_mov_b64 exec, -1

.LBB0_496:
	s_and_b32 s54, s58, 1
	s_waitcnt lgkmcnt(0)
	s_and_saveexec_b64 s[40:41], s[4:5]
	s_xor_b64 s[52:53], exec, s[40:41]
	s_cbranch_execz .LBB0_498
	v_mov_b32_e32 v220, 0x1f000
	v_add_u32_e32 v221, 0x1f010, v23
	v_mov_b32_e32 v222, 1
	s_cmp_eq_u32 s58, 0
	s_cbranch_scc1 .Lrdy_ok0
	s_waitcnt lgkmcnt(0)
	s_movk_i32 s33, 0x4000
.Lrdy_chk0:
	v_min3_u32 v228, v224, v225, v226
	v_min_u32_e32 v228, v228, v227
	s_nop 0
	v_readfirstlane_b32 s41, v228
	s_cmp_ge_u32 s41, s58
	s_cbranch_scc1 .Lrdy_ok0
	s_sub_u32 s33, s33, 1
	s_cmp_eq_u32 s33, 0
	s_cbranch_scc1 .Lrdy_ok0
	s_sleep 1
	ds_read_b128 v[224:227], v220
	s_waitcnt lgkmcnt(0)
	s_branch .Lrdy_chk0
.Lrdy_ok0:
	s_mov_b32 s11, s10
	s_mov_b32 s15, s14
	s_mov_b32 s35, s34
	s_mov_b32 s37, s36
	s_mov_b32 s43, s42
	s_mov_b32 s45, s44
	s_mul_i32 s40, s54, 0xa000
	s_mul_i32 s41, s54, 0xa00
	s_add_i32 s41, s41, 0x14000
	v_add_u32_e32 v29, s40, v24
	v_add_u32_e32 v31, v23, v22
	v_mul_u32_u24_e32 v31, 0x90, v31
	v_mov_b32_e32 v30, s41
	v_add_u32_e32 v31, s41, v31
	ds_read_b128 v[44:47], v29 offset:48
	ds_read_b128 v[64:67], v29 offset:1328
	ds_read_b128 v[40:43], v29 offset:32
	ds_read_b128 v[112:115], v31 offset:0
	ds_read_b128 v[32:35], v29 offset:0
	ds_read_b128 v[120:123], v30 offset:2304
	ds_read_b128 v[48:51], v29 offset:64
	ds_read_b128 v[60:63], v29 offset:1312
	ds_read_b128 v[52:55], v29 offset:1280
	ds_read_b128 v[36:39], v29 offset:16
	ds_read_b128 v[68:71], v29 offset:1344
	ds_read_b128 v[56:59], v29 offset:1296
	s_cmp_eq_u32 s58, 0
	s_cbranch_scc1 .Lscan_tail_skip0
	v_add_f32_e32 v206, v144, v145
	v_add_f32_e32 v207, v146, v147
	v_cndmask_b32_e64 v208, v204, v205, s[10:11]
	v_cndmask_b32_e64 v209, v205, v204, s[10:11]
	v_cndmask_b32_e64 v210, v206, v207, s[10:11]
	v_cndmask_b32_e64 v211, v207, v206, s[10:11]
	v_add_f32_dpp v212, v209, v208 quad_perm:[1,0,3,2] row_mask:0xf bank_mask:0xf bound_ctrl:1
	s_nop 0
	v_add_f32_dpp v213, v211, v210 quad_perm:[1,0,3,2] row_mask:0xf bank_mask:0xf bound_ctrl:1
	v_cndmask_b32_e64 v214, v212, v213, s[14:15]
	v_cndmask_b32_e64 v215, v213, v212, s[14:15]
	s_nop 1
	v_add_f32_dpp v216, v215, v214 quad_perm:[2,3,0,1] row_mask:0xf bank_mask:0xf bound_ctrl:1
	s_nop 1
	v_add_f32_dpp v216, v216, v216 row_ror:8 row_mask:0xf bank_mask:0xf bound_ctrl:1
	s_nop 1
	v_add_f32_dpp v216, v216, v216 row_ror:4 row_mask:0xf bank_mask:0xf bound_ctrl:1
	v_cndmask_b32_e64 v28, v28, v216, s[44:45]
	v_add_co_u32_e32 v218, vcc, 0x4cfc000, v12
	s_nop 1
	v_addc_co_u32_e32 v219, vcc, 0, v13, vcc
	global_store_dword v[218:219], v28, off
.Lscan_tail_skip0:
	s_waitcnt lgkmcnt(7)
	v_pk_mul_f32 v[132:133], v[16:17], v[44:45]
	v_pk_mul_f32 v[134:135], v[16:17], v[64:65]
	v_pk_fma_f32 v[132:133], v[18:19], v[46:47], v[132:133]
	v_pk_fma_f32 v[134:135], v[18:19], v[66:67], v[134:135]
	v_pk_mul_f32 v[136:137], v[112:113], v[40:41] op_sel_hi:[0,1]
	v_add_f32_e32 v148, v132, v133
	v_add_f32_e32 v149, v134, v135
	v_pk_mul_f32 v[138:139], v[112:113], v[42:43] op_sel_hi:[0,1]
	v_add_f32_dpp v148, v148, v148 quad_perm:[1,0,3,2] row_mask:0xf bank_mask:0xf bound_ctrl:1
	v_add_f32_dpp v149, v149, v149 quad_perm:[1,0,3,2] row_mask:0xf bank_mask:0xf bound_ctrl:1
	v_pk_fma_f32 v[136:137], v[16:17], v[32:33], v[136:137]
	v_add_f32_dpp v148, v148, v148 quad_perm:[2,3,0,1] row_mask:0xf bank_mask:0xf bound_ctrl:1
	v_add_f32_dpp v149, v149, v149 quad_perm:[2,3,0,1] row_mask:0xf bank_mask:0xf bound_ctrl:1
	v_pk_fma_f32 v[138:139], v[18:19], v[34:35], v[138:139]
	v_add_f32_dpp v148, v148, v148 row_half_mirror row_mask:0xf bank_mask:0xf bound_ctrl:1
	v_add_f32_dpp v149, v149, v149 row_half_mirror row_mask:0xf bank_mask:0xf bound_ctrl:1
	ds_read_b128 v[84:87], v29 offset:2608
	ds_read_b128 v[104:107], v29 offset:3888
	ds_read_b128 v[80:83], v29 offset:2592
	ds_read_b128 v[72:75], v29 offset:2560
	ds_read_b128 v[88:91], v29 offset:2624
	ds_read_b128 v[100:103], v29 offset:3872
	ds_read_b128 v[92:95], v29 offset:3840
	ds_read_b128 v[76:79], v29 offset:2576
	ds_read_b128 v[108:111], v29 offset:3904
	ds_read_b128 v[96:99], v29 offset:3856
	s_waitcnt lgkmcnt(10)
	v_pk_mul_f32 v[140:141], v[112:113], v[60:61] op_sel:[1,0] op_sel_hi:[1,1]
	v_add_f32_dpp v148, v148, v148 row_mirror row_mask:0xf bank_mask:0xf bound_ctrl:1
	v_add_f32_dpp v149, v149, v149 row_mirror row_mask:0xf bank_mask:0xf bound_ctrl:1
	v_pk_mul_f32 v[142:143], v[112:113], v[62:63] op_sel:[1,0] op_sel_hi:[1,1]
	v_fmac_f32_e32 v149, v112, v120
	v_pk_fma_f32 v[16:17], v[48:49], v[148:149], v[136:137] op_sel_hi:[1,0,1]
	v_pk_fma_f32 v[18:19], v[50:51], v[148:149], v[138:139] op_sel_hi:[1,0,1]
	v_pk_fma_f32 v[140:141], v[16:17], v[52:53], v[140:141]
	v_pk_mul_f32 v[144:145], v[16:17], v[36:37]
	v_pk_fma_f32 v[142:143], v[18:19], v[54:55], v[142:143]
	v_pk_fma_f32 v[144:145], v[18:19], v[38:39], v[144:145]
	v_pk_fma_f32 v[16:17], v[68:69], v[148:149], v[140:141] op_sel:[0,1,0] op_sel_hi:[1,1,1]
	v_pk_fma_f32 v[18:19], v[70:71], v[148:149], v[142:143] op_sel:[0,1,0] op_sel_hi:[1,1,1]
	v_pk_mul_f32 v[146:147], v[16:17], v[56:57]
	v_pk_fma_f32 v[146:147], v[18:19], v[58:59], v[146:147]
	s_waitcnt lgkmcnt(6)
	v_pk_mul_f32 v[132:133], v[16:17], v[84:85]
	v_pk_mul_f32 v[134:135], v[16:17], v[104:105]
	v_add_f32_e32 v200, v144, v145
	v_pk_fma_f32 v[132:133], v[18:19], v[86:87], v[132:133]
	v_pk_fma_f32 v[134:135], v[18:19], v[106:107], v[134:135]
	v_add_f32_e32 v201, v146, v147
	v_pk_mul_f32 v[136:137], v[114:115], v[80:81] op_sel_hi:[0,1]
	v_add_f32_e32 v148, v132, v133
	v_add_f32_e32 v149, v134, v135
	v_pk_mul_f32 v[138:139], v[114:115], v[82:83] op_sel_hi:[0,1]
	v_add_f32_dpp v148, v148, v148 quad_perm:[1,0,3,2] row_mask:0xf bank_mask:0xf bound_ctrl:1
	v_add_f32_dpp v149, v149, v149 quad_perm:[1,0,3,2] row_mask:0xf bank_mask:0xf bound_ctrl:1
	v_pk_fma_f32 v[136:137], v[16:17], v[72:73], v[136:137]
	v_add_f32_dpp v148, v148, v148 quad_perm:[2,3,0,1] row_mask:0xf bank_mask:0xf bound_ctrl:1
	v_add_f32_dpp v149, v149, v149 quad_perm:[2,3,0,1] row_mask:0xf bank_mask:0xf bound_ctrl:1
	v_pk_fma_f32 v[138:139], v[18:19], v[74:75], v[138:139]
	v_add_f32_dpp v148, v148, v148 row_half_mirror row_mask:0xf bank_mask:0xf bound_ctrl:1
	v_add_f32_dpp v149, v149, v149 row_half_mirror row_mask:0xf bank_mask:0xf bound_ctrl:1
	ds_read_b128 v[172:175], v29 offset:5168
	ds_read_b128 v[192:195], v29 offset:6448
	ds_read_b128 v[168:171], v29 offset:5152
	ds_read_b128 v[116:119], v31 offset:16
	ds_read_b128 v[160:163], v29 offset:5120
	ds_read_b128 v[176:179], v29 offset:5184
	ds_read_b128 v[188:191], v29 offset:6432
	ds_read_b128 v[180:183], v29 offset:6400
	ds_read_b128 v[164:167], v29 offset:5136
	ds_read_b128 v[196:199], v29 offset:6464
	ds_read_b128 v[184:187], v29 offset:6416
	s_waitcnt lgkmcnt(11)
	v_pk_mul_f32 v[140:141], v[114:115], v[100:101] op_sel:[1,0] op_sel_hi:[1,1]
	v_add_f32_dpp v148, v148, v148 row_mirror row_mask:0xf bank_mask:0xf bound_ctrl:1
	v_add_f32_dpp v149, v149, v149 row_mirror row_mask:0xf bank_mask:0xf bound_ctrl:1
	v_pk_mul_f32 v[142:143], v[114:115], v[102:103] op_sel:[1,0] op_sel_hi:[1,1]
	v_fmac_f32_e32 v149, v114, v121
	v_pk_fma_f32 v[16:17], v[88:89], v[148:149], v[136:137] op_sel_hi:[1,0,1]
	v_pk_fma_f32 v[18:19], v[90:91], v[148:149], v[138:139] op_sel_hi:[1,0,1]
	v_pk_fma_f32 v[140:141], v[16:17], v[92:93], v[140:141]
	v_pk_mul_f32 v[144:145], v[16:17], v[76:77]
	v_pk_fma_f32 v[142:143], v[18:19], v[94:95], v[142:143]
	v_pk_fma_f32 v[144:145], v[18:19], v[78:79], v[144:145]
	v_pk_fma_f32 v[16:17], v[108:109], v[148:149], v[140:141] op_sel:[0,1,0] op_sel_hi:[1,1,1]
	v_pk_fma_f32 v[18:19], v[110:111], v[148:149], v[142:143] op_sel:[0,1,0] op_sel_hi:[1,1,1]
	v_pk_mul_f32 v[146:147], v[16:17], v[96:97]
	v_pk_fma_f32 v[146:147], v[18:19], v[98:99], v[146:147]
	s_waitcnt lgkmcnt(6)
	v_pk_mul_f32 v[132:133], v[16:17], v[172:173]
	v_pk_mul_f32 v[134:135], v[16:17], v[192:193]
	v_add_f32_e32 v202, v144, v145
	v_pk_fma_f32 v[132:133], v[18:19], v[174:175], v[132:133]
	v_pk_fma_f32 v[134:135], v[18:19], v[194:195], v[134:135]
	v_add_f32_e32 v203, v146, v147
	v_pk_mul_f32 v[136:137], v[116:117], v[168:169] op_sel_hi:[0,1]
	v_add_f32_e32 v148, v132, v133
	v_cndmask_b32_e64 v208, v200, v201, s[10:11]
	v_add_f32_e32 v149, v134, v135
	v_pk_mul_f32 v[138:139], v[116:117], v[170:171] op_sel_hi:[0,1]
	v_cndmask_b32_e64 v209, v201, v200, s[10:11]
	v_add_f32_dpp v148, v148, v148 quad_perm:[1,0,3,2] row_mask:0xf bank_mask:0xf bound_ctrl:1
	v_add_f32_dpp v149, v149, v149 quad_perm:[1,0,3,2] row_mask:0xf bank_mask:0xf bound_ctrl:1
	v_cndmask_b32_e64 v210, v202, v203, s[10:11]
	v_pk_fma_f32 v[136:137], v[16:17], v[160:161], v[136:137]
	v_add_f32_dpp v148, v148, v148 quad_perm:[2,3,0,1] row_mask:0xf bank_mask:0xf bound_ctrl:1
	v_cndmask_b32_e64 v211, v203, v202, s[10:11]
	v_add_f32_dpp v149, v149, v149 quad_perm:[2,3,0,1] row_mask:0xf bank_mask:0xf bound_ctrl:1
	v_pk_fma_f32 v[138:139], v[18:19], v[162:163], v[138:139]
	v_add_f32_dpp v212, v209, v208 quad_perm:[1,0,3,2] row_mask:0xf bank_mask:0xf bound_ctrl:1
	v_add_f32_dpp v148, v148, v148 row_half_mirror row_mask:0xf bank_mask:0xf bound_ctrl:1
	v_add_f32_dpp v149, v149, v149 row_half_mirror row_mask:0xf bank_mask:0xf bound_ctrl:1
	v_add_f32_dpp v213, v211, v210 quad_perm:[1,0,3,2] row_mask:0xf bank_mask:0xf bound_ctrl:1
	ds_read_b128 v[44:47], v29 offset:7728
	ds_read_b128 v[64:67], v29 offset:9008
	ds_read_b128 v[40:43], v29 offset:7712
	ds_read_b128 v[32:35], v29 offset:7680
	ds_read_b128 v[48:51], v29 offset:7744
	ds_read_b128 v[60:63], v29 offset:8992
	ds_read_b128 v[52:55], v29 offset:8960
	ds_read_b128 v[36:39], v29 offset:7696
	ds_read_b128 v[68:71], v29 offset:9024
	ds_read_b128 v[56:59], v29 offset:8976
	s_waitcnt lgkmcnt(10)
	v_pk_mul_f32 v[140:141], v[116:117], v[188:189] op_sel:[1,0] op_sel_hi:[1,1]
	v_cndmask_b32_e64 v214, v212, v213, s[14:15]
	v_add_f32_dpp v148, v148, v148 row_mirror row_mask:0xf bank_mask:0xf bound_ctrl:1
	v_add_f32_dpp v149, v149, v149 row_mirror row_mask:0xf bank_mask:0xf bound_ctrl:1
	v_cndmask_b32_e64 v215, v213, v212, s[14:15]
	v_pk_mul_f32 v[142:143], v[116:117], v[190:191] op_sel:[1,0] op_sel_hi:[1,1]
	v_fmac_f32_e32 v149, v116, v122
	v_add_f32_dpp v216, v215, v214 quad_perm:[2,3,0,1] row_mask:0xf bank_mask:0xf bound_ctrl:1
	v_pk_fma_f32 v[16:17], v[176:177], v[148:149], v[136:137] op_sel_hi:[1,0,1]
	v_pk_fma_f32 v[18:19], v[178:179], v[148:149], v[138:139] op_sel_hi:[1,0,1]
	v_add_f32_dpp v216, v216, v216 row_ror:8 row_mask:0xf bank_mask:0xf bound_ctrl:1
	v_pk_fma_f32 v[140:141], v[16:17], v[180:181], v[140:141]
	v_pk_mul_f32 v[144:145], v[16:17], v[164:165]
	v_add_f32_dpp v216, v216, v216 row_ror:4 row_mask:0xf bank_mask:0xf bound_ctrl:1
	v_pk_fma_f32 v[142:143], v[18:19], v[182:183], v[142:143]
	v_pk_fma_f32 v[144:145], v[18:19], v[166:167], v[144:145]
	v_cndmask_b32_e64 v28, v28, v216, s[34:35]
	v_pk_fma_f32 v[16:17], v[196:197], v[148:149], v[140:141] op_sel:[0,1,0] op_sel_hi:[1,1,1]
	v_pk_fma_f32 v[18:19], v[198:199], v[148:149], v[142:143] op_sel:[0,1,0] op_sel_hi:[1,1,1]
	v_pk_mul_f32 v[146:147], v[16:17], v[184:185]
	v_pk_fma_f32 v[146:147], v[18:19], v[186:187], v[146:147]
	s_waitcnt lgkmcnt(6)
	v_pk_mul_f32 v[132:133], v[16:17], v[44:45]
	v_pk_mul_f32 v[134:135], v[16:17], v[64:65]
	v_add_f32_e32 v204, v144, v145
	v_pk_fma_f32 v[132:133], v[18:19], v[46:47], v[132:133]
	v_pk_fma_f32 v[134:135], v[18:19], v[66:67], v[134:135]
	v_add_f32_e32 v205, v146, v147
	v_pk_mul_f32 v[136:137], v[118:119], v[40:41] op_sel_hi:[0,1]
	v_add_f32_e32 v148, v132, v133
	v_add_f32_e32 v149, v134, v135
	v_pk_mul_f32 v[138:139], v[118:119], v[42:43] op_sel_hi:[0,1]
	v_add_f32_dpp v148, v148, v148 quad_perm:[1,0,3,2] row_mask:0xf bank_mask:0xf bound_ctrl:1
	v_add_f32_dpp v149, v149, v149 quad_perm:[1,0,3,2] row_mask:0xf bank_mask:0xf bound_ctrl:1
	v_pk_fma_f32 v[136:137], v[16:17], v[32:33], v[136:137]
	v_add_f32_dpp v148, v148, v148 quad_perm:[2,3,0,1] row_mask:0xf bank_mask:0xf bound_ctrl:1
	v_add_f32_dpp v149, v149, v149 quad_perm:[2,3,0,1] row_mask:0xf bank_mask:0xf bound_ctrl:1
	v_pk_fma_f32 v[138:139], v[18:19], v[34:35], v[138:139]
	v_add_f32_dpp v148, v148, v148 row_half_mirror row_mask:0xf bank_mask:0xf bound_ctrl:1
	v_add_f32_dpp v149, v149, v149 row_half_mirror row_mask:0xf bank_mask:0xf bound_ctrl:1
	ds_read_b128 v[84:87], v29 offset:10288
	ds_read_b128 v[104:107], v29 offset:11568
	ds_read_b128 v[80:83], v29 offset:10272
	ds_read_b128 v[112:115], v31 offset:32
	ds_read_b128 v[72:75], v29 offset:10240
	ds_read_b128 v[124:127], v30 offset:2320
	ds_read_b128 v[88:91], v29 offset:10304
	ds_read_b128 v[100:103], v29 offset:11552
	ds_read_b128 v[92:95], v29 offset:11520
	ds_read_b128 v[76:79], v29 offset:10256
	ds_read_b128 v[108:111], v29 offset:11584
	ds_read_b128 v[96:99], v29 offset:11536
	s_waitcnt lgkmcnt(12)
	v_pk_mul_f32 v[140:141], v[118:119], v[60:61] op_sel:[1,0] op_sel_hi:[1,1]
	v_add_f32_dpp v148, v148, v148 row_mirror row_mask:0xf bank_mask:0xf bound_ctrl:1
	v_add_f32_dpp v149, v149, v149 row_mirror row_mask:0xf bank_mask:0xf bound_ctrl:1
	v_pk_mul_f32 v[142:143], v[118:119], v[62:63] op_sel:[1,0] op_sel_hi:[1,1]
	v_fmac_f32_e32 v149, v118, v123
	v_pk_fma_f32 v[16:17], v[48:49], v[148:149], v[136:137] op_sel_hi:[1,0,1]
	v_pk_fma_f32 v[18:19], v[50:51], v[148:149], v[138:139] op_sel_hi:[1,0,1]
	v_pk_fma_f32 v[140:141], v[16:17], v[52:53], v[140:141]
	v_pk_mul_f32 v[144:145], v[16:17], v[36:37]
	v_pk_fma_f32 v[142:143], v[18:19], v[54:55], v[142:143]
	v_pk_fma_f32 v[144:145], v[18:19], v[38:39], v[144:145]
	v_pk_fma_f32 v[16:17], v[68:69], v[148:149], v[140:141] op_sel:[0,1,0] op_sel_hi:[1,1,1]
	v_pk_fma_f32 v[18:19], v[70:71], v[148:149], v[142:143] op_sel:[0,1,0] op_sel_hi:[1,1,1]
	v_pk_mul_f32 v[146:147], v[16:17], v[56:57]
	v_pk_fma_f32 v[146:147], v[18:19], v[58:59], v[146:147]
	s_waitcnt lgkmcnt(7)
	v_pk_mul_f32 v[132:133], v[16:17], v[84:85]
	v_pk_mul_f32 v[134:135], v[16:17], v[104:105]
	v_add_f32_e32 v206, v144, v145
	v_pk_fma_f32 v[132:133], v[18:19], v[86:87], v[132:133]
	v_pk_fma_f32 v[134:135], v[18:19], v[106:107], v[134:135]
	v_add_f32_e32 v207, v146, v147
	v_pk_mul_f32 v[136:137], v[112:113], v[80:81] op_sel_hi:[0,1]
	v_add_f32_e32 v148, v132, v133
	v_cndmask_b32_e64 v208, v204, v205, s[10:11]
	v_add_f32_e32 v149, v134, v135
	v_pk_mul_f32 v[138:139], v[112:113], v[82:83] op_sel_hi:[0,1]
	v_cndmask_b32_e64 v209, v205, v204, s[10:11]
	v_add_f32_dpp v148, v148, v148 quad_perm:[1,0,3,2] row_mask:0xf bank_mask:0xf bound_ctrl:1
	v_add_f32_dpp v149, v149, v149 quad_perm:[1,0,3,2] row_mask:0xf bank_mask:0xf bound_ctrl:1
	v_cndmask_b32_e64 v210, v206, v207, s[10:11]
	v_pk_fma_f32 v[136:137], v[16:17], v[72:73], v[136:137]
	v_add_f32_dpp v148, v148, v148 quad_perm:[2,3,0,1] row_mask:0xf bank_mask:0xf bound_ctrl:1
	v_cndmask_b32_e64 v211, v207, v206, s[10:11]
	v_add_f32_dpp v149, v149, v149 quad_perm:[2,3,0,1] row_mask:0xf bank_mask:0xf bound_ctrl:1
	v_pk_fma_f32 v[138:139], v[18:19], v[74:75], v[138:139]
	v_add_f32_dpp v212, v209, v208 quad_perm:[1,0,3,2] row_mask:0xf bank_mask:0xf bound_ctrl:1
	v_add_f32_dpp v148, v148, v148 row_half_mirror row_mask:0xf bank_mask:0xf bound_ctrl:1
	v_add_f32_dpp v149, v149, v149 row_half_mirror row_mask:0xf bank_mask:0xf bound_ctrl:1
	v_add_f32_dpp v213, v211, v210 quad_perm:[1,0,3,2] row_mask:0xf bank_mask:0xf bound_ctrl:1
	ds_read_b128 v[172:175], v29 offset:12848
	ds_read_b128 v[192:195], v29 offset:14128
	ds_read_b128 v[168:171], v29 offset:12832
	ds_read_b128 v[160:163], v29 offset:12800
	ds_read_b128 v[176:179], v29 offset:12864
	ds_read_b128 v[188:191], v29 offset:14112
	ds_read_b128 v[180:183], v29 offset:14080
	ds_read_b128 v[164:167], v29 offset:12816
	ds_read_b128 v[196:199], v29 offset:14144
	ds_read_b128 v[184:187], v29 offset:14096
	s_waitcnt lgkmcnt(10)
	v_pk_mul_f32 v[140:141], v[112:113], v[100:101] op_sel:[1,0] op_sel_hi:[1,1]
	v_cndmask_b32_e64 v214, v212, v213, s[14:15]
	v_add_f32_dpp v148, v148, v148 row_mirror row_mask:0xf bank_mask:0xf bound_ctrl:1
	v_add_f32_dpp v149, v149, v149 row_mirror row_mask:0xf bank_mask:0xf bound_ctrl:1
	v_cndmask_b32_e64 v215, v213, v212, s[14:15]
	v_pk_mul_f32 v[142:143], v[112:113], v[102:103] op_sel:[1,0] op_sel_hi:[1,1]
	v_fmac_f32_e32 v149, v112, v124
	v_add_f32_dpp v216, v215, v214 quad_perm:[2,3,0,1] row_mask:0xf bank_mask:0xf bound_ctrl:1
	v_pk_fma_f32 v[16:17], v[88:89], v[148:149], v[136:137] op_sel_hi:[1,0,1]
	v_pk_fma_f32 v[18:19], v[90:91], v[148:149], v[138:139] op_sel_hi:[1,0,1]
	v_add_f32_dpp v216, v216, v216 row_ror:8 row_mask:0xf bank_mask:0xf bound_ctrl:1
	v_pk_fma_f32 v[140:141], v[16:17], v[92:93], v[140:141]
	v_pk_mul_f32 v[144:145], v[16:17], v[76:77]
	v_add_f32_dpp v216, v216, v216 row_ror:4 row_mask:0xf bank_mask:0xf bound_ctrl:1
	v_pk_fma_f32 v[142:143], v[18:19], v[94:95], v[142:143]
	v_pk_fma_f32 v[144:145], v[18:19], v[78:79], v[144:145]
	v_cndmask_b32_e64 v28, v28, v216, s[36:37]
	v_pk_fma_f32 v[16:17], v[108:109], v[148:149], v[140:141] op_sel:[0,1,0] op_sel_hi:[1,1,1]
	v_pk_fma_f32 v[18:19], v[110:111], v[148:149], v[142:143] op_sel:[0,1,0] op_sel_hi:[1,1,1]
	v_pk_mul_f32 v[146:147], v[16:17], v[96:97]
	v_pk_fma_f32 v[146:147], v[18:19], v[98:99], v[146:147]
	s_waitcnt lgkmcnt(6)
	v_pk_mul_f32 v[132:133], v[16:17], v[172:173]
	v_pk_mul_f32 v[134:135], v[16:17], v[192:193]
	v_add_f32_e32 v200, v144, v145
	v_pk_fma_f32 v[132:133], v[18:19], v[174:175], v[132:133]
	v_pk_fma_f32 v[134:135], v[18:19], v[194:195], v[134:135]
	v_add_f32_e32 v201, v146, v147
	v_pk_mul_f32 v[136:137], v[114:115], v[168:169] op_sel_hi:[0,1]
	v_add_f32_e32 v148, v132, v133
	v_add_f32_e32 v149, v134, v135
	v_pk_mul_f32 v[138:139], v[114:115], v[170:171] op_sel_hi:[0,1]
	v_add_f32_dpp v148, v148, v148 quad_perm:[1,0,3,2] row_mask:0xf bank_mask:0xf bound_ctrl:1
	v_add_f32_dpp v149, v149, v149 quad_perm:[1,0,3,2] row_mask:0xf bank_mask:0xf bound_ctrl:1
	v_pk_fma_f32 v[136:137], v[16:17], v[160:161], v[136:137]
	v_add_f32_dpp v148, v148, v148 quad_perm:[2,3,0,1] row_mask:0xf bank_mask:0xf bound_ctrl:1
	v_add_f32_dpp v149, v149, v149 quad_perm:[2,3,0,1] row_mask:0xf bank_mask:0xf bound_ctrl:1
	v_pk_fma_f32 v[138:139], v[18:19], v[162:163], v[138:139]
	v_add_f32_dpp v148, v148, v148 row_half_mirror row_mask:0xf bank_mask:0xf bound_ctrl:1
	v_add_f32_dpp v149, v149, v149 row_half_mirror row_mask:0xf bank_mask:0xf bound_ctrl:1
	ds_read_b128 v[44:47], v29 offset:15408
	ds_read_b128 v[64:67], v29 offset:16688
	ds_read_b128 v[40:43], v29 offset:15392
	ds_read_b128 v[116:119], v31 offset:48
	ds_read_b128 v[32:35], v29 offset:15360
	ds_read_b128 v[48:51], v29 offset:15424
	ds_read_b128 v[60:63], v29 offset:16672
	ds_read_b128 v[52:55], v29 offset:16640
	ds_read_b128 v[36:39], v29 offset:15376
	ds_read_b128 v[68:71], v29 offset:16704
	ds_read_b128 v[56:59], v29 offset:16656
	s_waitcnt lgkmcnt(11)
	v_pk_mul_f32 v[140:141], v[114:115], v[188:189] op_sel:[1,0] op_sel_hi:[1,1]
	v_add_f32_dpp v148, v148, v148 row_mirror row_mask:0xf bank_mask:0xf bound_ctrl:1
	v_add_f32_dpp v149, v149, v149 row_mirror row_mask:0xf bank_mask:0xf bound_ctrl:1
	v_pk_mul_f32 v[142:143], v[114:115], v[190:191] op_sel:[1,0] op_sel_hi:[1,1]
	v_fmac_f32_e32 v149, v114, v125
	v_pk_fma_f32 v[16:17], v[176:177], v[148:149], v[136:137] op_sel_hi:[1,0,1]
	v_pk_fma_f32 v[18:19], v[178:179], v[148:149], v[138:139] op_sel_hi:[1,0,1]
	v_pk_fma_f32 v[140:141], v[16:17], v[180:181], v[140:141]
	v_pk_mul_f32 v[144:145], v[16:17], v[164:165]
	v_pk_fma_f32 v[142:143], v[18:19], v[182:183], v[142:143]
	v_pk_fma_f32 v[144:145], v[18:19], v[166:167], v[144:145]
	v_pk_fma_f32 v[16:17], v[196:197], v[148:149], v[140:141] op_sel:[0,1,0] op_sel_hi:[1,1,1]
	v_pk_fma_f32 v[18:19], v[198:199], v[148:149], v[142:143] op_sel:[0,1,0] op_sel_hi:[1,1,1]
	v_pk_mul_f32 v[146:147], v[16:17], v[184:185]
	v_pk_fma_f32 v[146:147], v[18:19], v[186:187], v[146:147]
	s_waitcnt lgkmcnt(6)
	v_pk_mul_f32 v[132:133], v[16:17], v[44:45]
	v_pk_mul_f32 v[134:135], v[16:17], v[64:65]
	v_add_f32_e32 v202, v144, v145
	v_pk_fma_f32 v[132:133], v[18:19], v[46:47], v[132:133]
	v_pk_fma_f32 v[134:135], v[18:19], v[66:67], v[134:135]
	v_add_f32_e32 v203, v146, v147
	v_pk_mul_f32 v[136:137], v[116:117], v[40:41] op_sel_hi:[0,1]
	v_add_f32_e32 v148, v132, v133
	v_cndmask_b32_e64 v208, v200, v201, s[10:11]
	v_add_f32_e32 v149, v134, v135
	v_pk_mul_f32 v[138:139], v[116:117], v[42:43] op_sel_hi:[0,1]
	v_cndmask_b32_e64 v209, v201, v200, s[10:11]
	v_add_f32_dpp v148, v148, v148 quad_perm:[1,0,3,2] row_mask:0xf bank_mask:0xf bound_ctrl:1
	v_add_f32_dpp v149, v149, v149 quad_perm:[1,0,3,2] row_mask:0xf bank_mask:0xf bound_ctrl:1
	v_cndmask_b32_e64 v210, v202, v203, s[10:11]
	v_pk_fma_f32 v[136:137], v[16:17], v[32:33], v[136:137]
	v_add_f32_dpp v148, v148, v148 quad_perm:[2,3,0,1] row_mask:0xf bank_mask:0xf bound_ctrl:1
	v_cndmask_b32_e64 v211, v203, v202, s[10:11]
	v_add_f32_dpp v149, v149, v149 quad_perm:[2,3,0,1] row_mask:0xf bank_mask:0xf bound_ctrl:1
	v_pk_fma_f32 v[138:139], v[18:19], v[34:35], v[138:139]
	v_add_f32_dpp v212, v209, v208 quad_perm:[1,0,3,2] row_mask:0xf bank_mask:0xf bound_ctrl:1
	v_add_f32_dpp v148, v148, v148 row_half_mirror row_mask:0xf bank_mask:0xf bound_ctrl:1
	v_add_f32_dpp v149, v149, v149 row_half_mirror row_mask:0xf bank_mask:0xf bound_ctrl:1
	v_add_f32_dpp v213, v211, v210 quad_perm:[1,0,3,2] row_mask:0xf bank_mask:0xf bound_ctrl:1
	ds_read_b128 v[84:87], v29 offset:17968
	ds_read_b128 v[104:107], v29 offset:19248
	ds_read_b128 v[80:83], v29 offset:17952
	ds_read_b128 v[72:75], v29 offset:17920
	ds_read_b128 v[88:91], v29 offset:17984
	ds_read_b128 v[100:103], v29 offset:19232
	ds_read_b128 v[92:95], v29 offset:19200
	ds_read_b128 v[76:79], v29 offset:17936
	ds_read_b128 v[108:111], v29 offset:19264
	ds_read_b128 v[96:99], v29 offset:19216
	s_waitcnt lgkmcnt(10)
	v_pk_mul_f32 v[140:141], v[116:117], v[60:61] op_sel:[1,0] op_sel_hi:[1,1]
	v_cndmask_b32_e64 v214, v212, v213, s[14:15]
	v_add_f32_dpp v148, v148, v148 row_mirror row_mask:0xf bank_mask:0xf bound_ctrl:1
	v_add_f32_dpp v149, v149, v149 row_mirror row_mask:0xf bank_mask:0xf bound_ctrl:1
	v_cndmask_b32_e64 v215, v213, v212, s[14:15]
	v_pk_mul_f32 v[142:143], v[116:117], v[62:63] op_sel:[1,0] op_sel_hi:[1,1]
	v_fmac_f32_e32 v149, v116, v126
	v_add_f32_dpp v216, v215, v214 quad_perm:[2,3,0,1] row_mask:0xf bank_mask:0xf bound_ctrl:1
	v_pk_fma_f32 v[16:17], v[48:49], v[148:149], v[136:137] op_sel_hi:[1,0,1]
	v_pk_fma_f32 v[18:19], v[50:51], v[148:149], v[138:139] op_sel_hi:[1,0,1]
	v_add_f32_dpp v216, v216, v216 row_ror:8 row_mask:0xf bank_mask:0xf bound_ctrl:1
	v_pk_fma_f32 v[140:141], v[16:17], v[52:53], v[140:141]
	v_pk_mul_f32 v[144:145], v[16:17], v[36:37]
	v_add_f32_dpp v216, v216, v216 row_ror:4 row_mask:0xf bank_mask:0xf bound_ctrl:1
	v_pk_fma_f32 v[142:143], v[18:19], v[54:55], v[142:143]
	v_pk_fma_f32 v[144:145], v[18:19], v[38:39], v[144:145]
	v_cndmask_b32_e64 v28, v28, v216, s[42:43]
	v_pk_fma_f32 v[16:17], v[68:69], v[148:149], v[140:141] op_sel:[0,1,0] op_sel_hi:[1,1,1]
	v_pk_fma_f32 v[18:19], v[70:71], v[148:149], v[142:143] op_sel:[0,1,0] op_sel_hi:[1,1,1]
	v_pk_mul_f32 v[146:147], v[16:17], v[56:57]
	v_pk_fma_f32 v[146:147], v[18:19], v[58:59], v[146:147]
	s_waitcnt lgkmcnt(6)
	v_pk_mul_f32 v[132:133], v[16:17], v[84:85]
	v_pk_mul_f32 v[134:135], v[16:17], v[104:105]
	v_add_f32_e32 v204, v144, v145
	v_pk_fma_f32 v[132:133], v[18:19], v[86:87], v[132:133]
	v_pk_fma_f32 v[134:135], v[18:19], v[106:107], v[134:135]
	v_add_f32_e32 v205, v146, v147
	v_pk_mul_f32 v[136:137], v[118:119], v[80:81] op_sel_hi:[0,1]
	v_add_f32_e32 v148, v132, v133
	v_add_f32_e32 v149, v134, v135
	v_pk_mul_f32 v[138:139], v[118:119], v[82:83] op_sel_hi:[0,1]
	v_add_f32_dpp v148, v148, v148 quad_perm:[1,0,3,2] row_mask:0xf bank_mask:0xf bound_ctrl:1
	v_add_f32_dpp v149, v149, v149 quad_perm:[1,0,3,2] row_mask:0xf bank_mask:0xf bound_ctrl:1
	v_pk_fma_f32 v[136:137], v[16:17], v[72:73], v[136:137]
	v_add_f32_dpp v148, v148, v148 quad_perm:[2,3,0,1] row_mask:0xf bank_mask:0xf bound_ctrl:1
	v_add_f32_dpp v149, v149, v149 quad_perm:[2,3,0,1] row_mask:0xf bank_mask:0xf bound_ctrl:1
	v_pk_fma_f32 v[138:139], v[18:19], v[74:75], v[138:139]
	v_add_f32_dpp v148, v148, v148 row_half_mirror row_mask:0xf bank_mask:0xf bound_ctrl:1
	v_add_f32_dpp v149, v149, v149 row_half_mirror row_mask:0xf bank_mask:0xf bound_ctrl:1
	ds_read_b128 v[172:175], v29 offset:20528
	ds_read_b128 v[192:195], v29 offset:21808
	ds_read_b128 v[168:171], v29 offset:20512
	ds_read_b128 v[112:115], v31 offset:64
	ds_read_b128 v[160:163], v29 offset:20480
	ds_read_b128 v[120:123], v30 offset:2336
	ds_read_b128 v[176:179], v29 offset:20544
	ds_read_b128 v[188:191], v29 offset:21792
	ds_read_b128 v[180:183], v29 offset:21760
	ds_read_b128 v[164:167], v29 offset:20496
	ds_read_b128 v[196:199], v29 offset:21824
	ds_read_b128 v[184:187], v29 offset:21776
	s_waitcnt lgkmcnt(12)
	v_pk_mul_f32 v[140:141], v[118:119], v[100:101] op_sel:[1,0] op_sel_hi:[1,1]
	v_add_f32_dpp v148, v148, v148 row_mirror row_mask:0xf bank_mask:0xf bound_ctrl:1
	v_add_f32_dpp v149, v149, v149 row_mirror row_mask:0xf bank_mask:0xf bound_ctrl:1
	v_pk_mul_f32 v[142:143], v[118:119], v[102:103] op_sel:[1,0] op_sel_hi:[1,1]
	v_fmac_f32_e32 v149, v118, v127
	v_pk_fma_f32 v[16:17], v[88:89], v[148:149], v[136:137] op_sel_hi:[1,0,1]
	v_pk_fma_f32 v[18:19], v[90:91], v[148:149], v[138:139] op_sel_hi:[1,0,1]
	v_pk_fma_f32 v[140:141], v[16:17], v[92:93], v[140:141]
	v_pk_mul_f32 v[144:145], v[16:17], v[76:77]
	v_pk_fma_f32 v[142:143], v[18:19], v[94:95], v[142:143]
	v_pk_fma_f32 v[144:145], v[18:19], v[78:79], v[144:145]
	v_pk_fma_f32 v[16:17], v[108:109], v[148:149], v[140:141] op_sel:[0,1,0] op_sel_hi:[1,1,1]
	v_pk_fma_f32 v[18:19], v[110:111], v[148:149], v[142:143] op_sel:[0,1,0] op_sel_hi:[1,1,1]
	v_pk_mul_f32 v[146:147], v[16:17], v[96:97]
	v_pk_fma_f32 v[146:147], v[18:19], v[98:99], v[146:147]
	s_waitcnt lgkmcnt(7)
	v_pk_mul_f32 v[132:133], v[16:17], v[172:173]
	v_pk_mul_f32 v[134:135], v[16:17], v[192:193]
	v_add_f32_e32 v206, v144, v145
	v_pk_fma_f32 v[132:133], v[18:19], v[174:175], v[132:133]
	v_pk_fma_f32 v[134:135], v[18:19], v[194:195], v[134:135]
	v_add_f32_e32 v207, v146, v147
	v_pk_mul_f32 v[136:137], v[112:113], v[168:169] op_sel_hi:[0,1]
	v_add_f32_e32 v148, v132, v133
	v_cndmask_b32_e64 v208, v204, v205, s[10:11]
	v_add_f32_e32 v149, v134, v135
	v_pk_mul_f32 v[138:139], v[112:113], v[170:171] op_sel_hi:[0,1]
	v_cndmask_b32_e64 v209, v205, v204, s[10:11]
	v_add_f32_dpp v148, v148, v148 quad_perm:[1,0,3,2] row_mask:0xf bank_mask:0xf bound_ctrl:1
	v_add_f32_dpp v149, v149, v149 quad_perm:[1,0,3,2] row_mask:0xf bank_mask:0xf bound_ctrl:1
	v_cndmask_b32_e64 v210, v206, v207, s[10:11]
	v_pk_fma_f32 v[136:137], v[16:17], v[160:161], v[136:137]
	v_add_f32_dpp v148, v148, v148 quad_perm:[2,3,0,1] row_mask:0xf bank_mask:0xf bound_ctrl:1
	v_cndmask_b32_e64 v211, v207, v206, s[10:11]
	v_add_f32_dpp v149, v149, v149 quad_perm:[2,3,0,1] row_mask:0xf bank_mask:0xf bound_ctrl:1
	v_pk_fma_f32 v[138:139], v[18:19], v[162:163], v[138:139]
	v_add_f32_dpp v212, v209, v208 quad_perm:[1,0,3,2] row_mask:0xf bank_mask:0xf bound_ctrl:1
	v_add_f32_dpp v148, v148, v148 row_half_mirror row_mask:0xf bank_mask:0xf bound_ctrl:1
	v_add_f32_dpp v149, v149, v149 row_half_mirror row_mask:0xf bank_mask:0xf bound_ctrl:1
	v_add_f32_dpp v213, v211, v210 quad_perm:[1,0,3,2] row_mask:0xf bank_mask:0xf bound_ctrl:1
	ds_read_b128 v[44:47], v29 offset:23088
	ds_read_b128 v[64:67], v29 offset:24368
	ds_read_b128 v[40:43], v29 offset:23072
	ds_read_b128 v[32:35], v29 offset:23040
	ds_read_b128 v[48:51], v29 offset:23104
	ds_read_b128 v[60:63], v29 offset:24352
	ds_read_b128 v[52:55], v29 offset:24320
	ds_read_b128 v[36:39], v29 offset:23056
	ds_read_b128 v[68:71], v29 offset:24384
	ds_read_b128 v[56:59], v29 offset:24336
	s_waitcnt lgkmcnt(10)
	v_pk_mul_f32 v[140:141], v[112:113], v[188:189] op_sel:[1,0] op_sel_hi:[1,1]
	v_cndmask_b32_e64 v214, v212, v213, s[14:15]
	v_add_f32_dpp v148, v148, v148 row_mirror row_mask:0xf bank_mask:0xf bound_ctrl:1
	v_add_f32_dpp v149, v149, v149 row_mirror row_mask:0xf bank_mask:0xf bound_ctrl:1
	v_cndmask_b32_e64 v215, v213, v212, s[14:15]
	v_pk_mul_f32 v[142:143], v[112:113], v[190:191] op_sel:[1,0] op_sel_hi:[1,1]
	v_fmac_f32_e32 v149, v112, v120
	v_add_f32_dpp v216, v215, v214 quad_perm:[2,3,0,1] row_mask:0xf bank_mask:0xf bound_ctrl:1
	v_pk_fma_f32 v[16:17], v[176:177], v[148:149], v[136:137] op_sel_hi:[1,0,1]
	v_pk_fma_f32 v[18:19], v[178:179], v[148:149], v[138:139] op_sel_hi:[1,0,1]
	v_add_f32_dpp v216, v216, v216 row_ror:8 row_mask:0xf bank_mask:0xf bound_ctrl:1
	v_pk_fma_f32 v[140:141], v[16:17], v[180:181], v[140:141]
	v_pk_mul_f32 v[144:145], v[16:17], v[164:165]
	v_add_f32_dpp v216, v216, v216 row_ror:4 row_mask:0xf bank_mask:0xf bound_ctrl:1
	v_pk_fma_f32 v[142:143], v[18:19], v[182:183], v[142:143]
	v_pk_fma_f32 v[144:145], v[18:19], v[166:167], v[144:145]
	v_cndmask_b32_e64 v28, v28, v216, s[44:45]
	v_pk_fma_f32 v[16:17], v[196:197], v[148:149], v[140:141] op_sel:[0,1,0] op_sel_hi:[1,1,1]
	v_pk_fma_f32 v[18:19], v[198:199], v[148:149], v[142:143] op_sel:[0,1,0] op_sel_hi:[1,1,1]
	v_add_co_u32_e32 v218, vcc, s59, v12
	v_pk_mul_f32 v[146:147], v[16:17], v[184:185]
	v_pk_fma_f32 v[146:147], v[18:19], v[186:187], v[146:147]
	s_nop 1
	v_addc_co_u32_e32 v219, vcc, 0, v13, vcc
	global_store_dword v[218:219], v28, off
	s_waitcnt lgkmcnt(6)
	v_pk_mul_f32 v[132:133], v[16:17], v[44:45]
	v_pk_mul_f32 v[134:135], v[16:17], v[64:65]
	v_add_f32_e32 v200, v144, v145
	v_pk_fma_f32 v[132:133], v[18:19], v[46:47], v[132:133]
	v_pk_fma_f32 v[134:135], v[18:19], v[66:67], v[134:135]
	v_add_f32_e32 v201, v146, v147
	v_pk_mul_f32 v[136:137], v[114:115], v[40:41] op_sel_hi:[0,1]
	v_add_f32_e32 v148, v132, v133
	v_add_f32_e32 v149, v134, v135
	v_pk_mul_f32 v[138:139], v[114:115], v[42:43] op_sel_hi:[0,1]
	v_add_f32_dpp v148, v148, v148 quad_perm:[1,0,3,2] row_mask:0xf bank_mask:0xf bound_ctrl:1
	v_add_f32_dpp v149, v149, v149 quad_perm:[1,0,3,2] row_mask:0xf bank_mask:0xf bound_ctrl:1
	v_pk_fma_f32 v[136:137], v[16:17], v[32:33], v[136:137]
	v_add_f32_dpp v148, v148, v148 quad_perm:[2,3,0,1] row_mask:0xf bank_mask:0xf bound_ctrl:1
	v_add_f32_dpp v149, v149, v149 quad_perm:[2,3,0,1] row_mask:0xf bank_mask:0xf bound_ctrl:1
	v_pk_fma_f32 v[138:139], v[18:19], v[34:35], v[138:139]
	v_add_f32_dpp v148, v148, v148 row_half_mirror row_mask:0xf bank_mask:0xf bound_ctrl:1
	v_add_f32_dpp v149, v149, v149 row_half_mirror row_mask:0xf bank_mask:0xf bound_ctrl:1
	ds_read_b128 v[84:87], v29 offset:25648
	ds_read_b128 v[104:107], v29 offset:26928
	ds_read_b128 v[80:83], v29 offset:25632
	ds_read_b128 v[116:119], v31 offset:80
	ds_read_b128 v[72:75], v29 offset:25600
	ds_read_b128 v[88:91], v29 offset:25664
	ds_read_b128 v[100:103], v29 offset:26912
	ds_read_b128 v[92:95], v29 offset:26880
	ds_read_b128 v[76:79], v29 offset:25616
	ds_read_b128 v[108:111], v29 offset:26944
	ds_read_b128 v[96:99], v29 offset:26896
	s_waitcnt lgkmcnt(11)
	v_pk_mul_f32 v[140:141], v[114:115], v[60:61] op_sel:[1,0] op_sel_hi:[1,1]
	v_add_f32_dpp v148, v148, v148 row_mirror row_mask:0xf bank_mask:0xf bound_ctrl:1
	v_add_f32_dpp v149, v149, v149 row_mirror row_mask:0xf bank_mask:0xf bound_ctrl:1
	v_pk_mul_f32 v[142:143], v[114:115], v[62:63] op_sel:[1,0] op_sel_hi:[1,1]
	v_fmac_f32_e32 v149, v114, v121
	v_pk_fma_f32 v[16:17], v[48:49], v[148:149], v[136:137] op_sel_hi:[1,0,1]
	v_pk_fma_f32 v[18:19], v[50:51], v[148:149], v[138:139] op_sel_hi:[1,0,1]
	v_pk_fma_f32 v[140:141], v[16:17], v[52:53], v[140:141]
	v_pk_mul_f32 v[144:145], v[16:17], v[36:37]
	v_pk_fma_f32 v[142:143], v[18:19], v[54:55], v[142:143]
	v_pk_fma_f32 v[144:145], v[18:19], v[38:39], v[144:145]
	v_pk_fma_f32 v[16:17], v[68:69], v[148:149], v[140:141] op_sel:[0,1,0] op_sel_hi:[1,1,1]
	v_pk_fma_f32 v[18:19], v[70:71], v[148:149], v[142:143] op_sel:[0,1,0] op_sel_hi:[1,1,1]
	v_pk_mul_f32 v[146:147], v[16:17], v[56:57]
	v_pk_fma_f32 v[146:147], v[18:19], v[58:59], v[146:147]
	s_waitcnt lgkmcnt(6)
	v_pk_mul_f32 v[132:133], v[16:17], v[84:85]
	v_pk_mul_f32 v[134:135], v[16:17], v[104:105]
	v_add_f32_e32 v202, v144, v145
	v_pk_fma_f32 v[132:133], v[18:19], v[86:87], v[132:133]
	v_pk_fma_f32 v[134:135], v[18:19], v[106:107], v[134:135]
	v_add_f32_e32 v203, v146, v147
	v_pk_mul_f32 v[136:137], v[116:117], v[80:81] op_sel_hi:[0,1]
	v_add_f32_e32 v148, v132, v133
	v_cndmask_b32_e64 v208, v200, v201, s[10:11]
	v_add_f32_e32 v149, v134, v135
	v_pk_mul_f32 v[138:139], v[116:117], v[82:83] op_sel_hi:[0,1]
	v_cndmask_b32_e64 v209, v201, v200, s[10:11]
	v_add_f32_dpp v148, v148, v148 quad_perm:[1,0,3,2] row_mask:0xf bank_mask:0xf bound_ctrl:1
	v_add_f32_dpp v149, v149, v149 quad_perm:[1,0,3,2] row_mask:0xf bank_mask:0xf bound_ctrl:1
	v_cndmask_b32_e64 v210, v202, v203, s[10:11]
	v_pk_fma_f32 v[136:137], v[16:17], v[72:73], v[136:137]
	v_add_f32_dpp v148, v148, v148 quad_perm:[2,3,0,1] row_mask:0xf bank_mask:0xf bound_ctrl:1
	v_cndmask_b32_e64 v211, v203, v202, s[10:11]
	v_add_f32_dpp v149, v149, v149 quad_perm:[2,3,0,1] row_mask:0xf bank_mask:0xf bound_ctrl:1
	v_pk_fma_f32 v[138:139], v[18:19], v[74:75], v[138:139]
	v_add_f32_dpp v212, v209, v208 quad_perm:[1,0,3,2] row_mask:0xf bank_mask:0xf bound_ctrl:1
	v_add_f32_dpp v148, v148, v148 row_half_mirror row_mask:0xf bank_mask:0xf bound_ctrl:1
	v_add_f32_dpp v149, v149, v149 row_half_mirror row_mask:0xf bank_mask:0xf bound_ctrl:1
	v_add_f32_dpp v213, v211, v210 quad_perm:[1,0,3,2] row_mask:0xf bank_mask:0xf bound_ctrl:1
	ds_read_b128 v[172:175], v29 offset:28208
	ds_read_b128 v[192:195], v29 offset:29488
	ds_read_b128 v[168:171], v29 offset:28192
	ds_read_b128 v[160:163], v29 offset:28160
	ds_read_b128 v[176:179], v29 offset:28224
	ds_read_b128 v[188:191], v29 offset:29472
	ds_read_b128 v[180:183], v29 offset:29440
	ds_read_b128 v[164:167], v29 offset:28176
	ds_read_b128 v[196:199], v29 offset:29504
	ds_read_b128 v[184:187], v29 offset:29456
	s_waitcnt lgkmcnt(10)
	v_pk_mul_f32 v[140:141], v[116:117], v[100:101] op_sel:[1,0] op_sel_hi:[1,1]
	v_cndmask_b32_e64 v214, v212, v213, s[14:15]
	v_add_f32_dpp v148, v148, v148 row_mirror row_mask:0xf bank_mask:0xf bound_ctrl:1
	v_add_f32_dpp v149, v149, v149 row_mirror row_mask:0xf bank_mask:0xf bound_ctrl:1
	v_cndmask_b32_e64 v215, v213, v212, s[14:15]
	v_pk_mul_f32 v[142:143], v[116:117], v[102:103] op_sel:[1,0] op_sel_hi:[1,1]
	v_fmac_f32_e32 v149, v116, v122
	v_add_f32_dpp v216, v215, v214 quad_perm:[2,3,0,1] row_mask:0xf bank_mask:0xf bound_ctrl:1
	v_pk_fma_f32 v[16:17], v[88:89], v[148:149], v[136:137] op_sel_hi:[1,0,1]
	v_pk_fma_f32 v[18:19], v[90:91], v[148:149], v[138:139] op_sel_hi:[1,0,1]
	v_add_f32_dpp v216, v216, v216 row_ror:8 row_mask:0xf bank_mask:0xf bound_ctrl:1
	v_pk_fma_f32 v[140:141], v[16:17], v[92:93], v[140:141]
	v_pk_mul_f32 v[144:145], v[16:17], v[76:77]
	v_add_f32_dpp v216, v216, v216 row_ror:4 row_mask:0xf bank_mask:0xf bound_ctrl:1
	v_pk_fma_f32 v[142:143], v[18:19], v[94:95], v[142:143]
	v_pk_fma_f32 v[144:145], v[18:19], v[78:79], v[144:145]
	v_cndmask_b32_e64 v28, v28, v216, s[34:35]
	v_pk_fma_f32 v[16:17], v[108:109], v[148:149], v[140:141] op_sel:[0,1,0] op_sel_hi:[1,1,1]
	v_pk_fma_f32 v[18:19], v[110:111], v[148:149], v[142:143] op_sel:[0,1,0] op_sel_hi:[1,1,1]
	v_pk_mul_f32 v[146:147], v[16:17], v[96:97]
	v_pk_fma_f32 v[146:147], v[18:19], v[98:99], v[146:147]
	s_waitcnt lgkmcnt(6)
	v_pk_mul_f32 v[132:133], v[16:17], v[172:173]
	v_pk_mul_f32 v[134:135], v[16:17], v[192:193]
	v_add_f32_e32 v204, v144, v145
	v_pk_fma_f32 v[132:133], v[18:19], v[174:175], v[132:133]
	v_pk_fma_f32 v[134:135], v[18:19], v[194:195], v[134:135]
	v_add_f32_e32 v205, v146, v147
	v_pk_mul_f32 v[136:137], v[118:119], v[168:169] op_sel_hi:[0,1]
	v_add_f32_e32 v148, v132, v133
	v_add_f32_e32 v149, v134, v135
	v_pk_mul_f32 v[138:139], v[118:119], v[170:171] op_sel_hi:[0,1]
	v_add_f32_dpp v148, v148, v148 quad_perm:[1,0,3,2] row_mask:0xf bank_mask:0xf bound_ctrl:1
	v_add_f32_dpp v149, v149, v149 quad_perm:[1,0,3,2] row_mask:0xf bank_mask:0xf bound_ctrl:1
	v_pk_fma_f32 v[136:137], v[16:17], v[160:161], v[136:137]
	v_add_f32_dpp v148, v148, v148 quad_perm:[2,3,0,1] row_mask:0xf bank_mask:0xf bound_ctrl:1
	v_add_f32_dpp v149, v149, v149 quad_perm:[2,3,0,1] row_mask:0xf bank_mask:0xf bound_ctrl:1
	v_pk_fma_f32 v[138:139], v[18:19], v[162:163], v[138:139]
	v_add_f32_dpp v148, v148, v148 row_half_mirror row_mask:0xf bank_mask:0xf bound_ctrl:1
	v_add_f32_dpp v149, v149, v149 row_half_mirror row_mask:0xf bank_mask:0xf bound_ctrl:1
	ds_read_b128 v[44:47], v29 offset:30768
	ds_read_b128 v[64:67], v29 offset:32048
	ds_read_b128 v[40:43], v29 offset:30752
	ds_read_b128 v[112:115], v31 offset:96
	ds_read_b128 v[32:35], v29 offset:30720
	ds_read_b128 v[124:127], v30 offset:2352
	ds_read_b128 v[48:51], v29 offset:30784
	ds_read_b128 v[60:63], v29 offset:32032
	ds_read_b128 v[52:55], v29 offset:32000
	ds_read_b128 v[36:39], v29 offset:30736
	ds_read_b128 v[68:71], v29 offset:32064
	ds_read_b128 v[56:59], v29 offset:32016
	s_waitcnt lgkmcnt(12)
	v_pk_mul_f32 v[140:141], v[118:119], v[188:189] op_sel:[1,0] op_sel_hi:[1,1]
	v_add_f32_dpp v148, v148, v148 row_mirror row_mask:0xf bank_mask:0xf bound_ctrl:1
	v_add_f32_dpp v149, v149, v149 row_mirror row_mask:0xf bank_mask:0xf bound_ctrl:1
	v_pk_mul_f32 v[142:143], v[118:119], v[190:191] op_sel:[1,0] op_sel_hi:[1,1]
	v_fmac_f32_e32 v149, v118, v123
	v_pk_fma_f32 v[16:17], v[176:177], v[148:149], v[136:137] op_sel_hi:[1,0,1]
	v_pk_fma_f32 v[18:19], v[178:179], v[148:149], v[138:139] op_sel_hi:[1,0,1]
	v_pk_fma_f32 v[140:141], v[16:17], v[180:181], v[140:141]
	v_pk_mul_f32 v[144:145], v[16:17], v[164:165]
	v_pk_fma_f32 v[142:143], v[18:19], v[182:183], v[142:143]
	v_pk_fma_f32 v[144:145], v[18:19], v[166:167], v[144:145]
	v_pk_fma_f32 v[16:17], v[196:197], v[148:149], v[140:141] op_sel:[0,1,0] op_sel_hi:[1,1,1]
	v_pk_fma_f32 v[18:19], v[198:199], v[148:149], v[142:143] op_sel:[0,1,0] op_sel_hi:[1,1,1]
	v_pk_mul_f32 v[146:147], v[16:17], v[184:185]
	v_pk_fma_f32 v[146:147], v[18:19], v[186:187], v[146:147]
	s_waitcnt lgkmcnt(7)
	v_pk_mul_f32 v[132:133], v[16:17], v[44:45]
	v_pk_mul_f32 v[134:135], v[16:17], v[64:65]
	v_add_f32_e32 v206, v144, v145
	v_pk_fma_f32 v[132:133], v[18:19], v[46:47], v[132:133]
	v_pk_fma_f32 v[134:135], v[18:19], v[66:67], v[134:135]
	v_add_f32_e32 v207, v146, v147
	v_pk_mul_f32 v[136:137], v[112:113], v[40:41] op_sel_hi:[0,1]
	v_add_f32_e32 v148, v132, v133
	v_cndmask_b32_e64 v208, v204, v205, s[10:11]
	v_add_f32_e32 v149, v134, v135
	v_pk_mul_f32 v[138:139], v[112:113], v[42:43] op_sel_hi:[0,1]
	v_cndmask_b32_e64 v209, v205, v204, s[10:11]
	v_add_f32_dpp v148, v148, v148 quad_perm:[1,0,3,2] row_mask:0xf bank_mask:0xf bound_ctrl:1
	v_add_f32_dpp v149, v149, v149 quad_perm:[1,0,3,2] row_mask:0xf bank_mask:0xf bound_ctrl:1
	v_cndmask_b32_e64 v210, v206, v207, s[10:11]
	v_pk_fma_f32 v[136:137], v[16:17], v[32:33], v[136:137]
	v_add_f32_dpp v148, v148, v148 quad_perm:[2,3,0,1] row_mask:0xf bank_mask:0xf bound_ctrl:1
	v_cndmask_b32_e64 v211, v207, v206, s[10:11]
	v_add_f32_dpp v149, v149, v149 quad_perm:[2,3,0,1] row_mask:0xf bank_mask:0xf bound_ctrl:1
	v_pk_fma_f32 v[138:139], v[18:19], v[34:35], v[138:139]
	v_add_f32_dpp v212, v209, v208 quad_perm:[1,0,3,2] row_mask:0xf bank_mask:0xf bound_ctrl:1
	v_add_f32_dpp v148, v148, v148 row_half_mirror row_mask:0xf bank_mask:0xf bound_ctrl:1
	v_add_f32_dpp v149, v149, v149 row_half_mirror row_mask:0xf bank_mask:0xf bound_ctrl:1
	v_add_f32_dpp v213, v211, v210 quad_perm:[1,0,3,2] row_mask:0xf bank_mask:0xf bound_ctrl:1
	ds_read_b128 v[84:87], v29 offset:33328
	ds_read_b128 v[104:107], v29 offset:34608
	ds_read_b128 v[80:83], v29 offset:33312
	ds_read_b128 v[72:75], v29 offset:33280
	ds_read_b128 v[88:91], v29 offset:33344
	ds_read_b128 v[100:103], v29 offset:34592
	ds_read_b128 v[92:95], v29 offset:34560
	ds_read_b128 v[76:79], v29 offset:33296
	ds_read_b128 v[108:111], v29 offset:34624
	ds_read_b128 v[96:99], v29 offset:34576
	s_waitcnt lgkmcnt(10)
	v_pk_mul_f32 v[140:141], v[112:113], v[60:61] op_sel:[1,0] op_sel_hi:[1,1]
	v_cndmask_b32_e64 v214, v212, v213, s[14:15]
	v_add_f32_dpp v148, v148, v148 row_mirror row_mask:0xf bank_mask:0xf bound_ctrl:1
	v_add_f32_dpp v149, v149, v149 row_mirror row_mask:0xf bank_mask:0xf bound_ctrl:1
	v_cndmask_b32_e64 v215, v213, v212, s[14:15]
	v_pk_mul_f32 v[142:143], v[112:113], v[62:63] op_sel:[1,0] op_sel_hi:[1,1]
	v_fmac_f32_e32 v149, v112, v124
	v_add_f32_dpp v216, v215, v214 quad_perm:[2,3,0,1] row_mask:0xf bank_mask:0xf bound_ctrl:1
	v_pk_fma_f32 v[16:17], v[48:49], v[148:149], v[136:137] op_sel_hi:[1,0,1]
	v_pk_fma_f32 v[18:19], v[50:51], v[148:149], v[138:139] op_sel_hi:[1,0,1]
	v_add_f32_dpp v216, v216, v216 row_ror:8 row_mask:0xf bank_mask:0xf bound_ctrl:1
	v_pk_fma_f32 v[140:141], v[16:17], v[52:53], v[140:141]
	v_pk_mul_f32 v[144:145], v[16:17], v[36:37]
	v_add_f32_dpp v216, v216, v216 row_ror:4 row_mask:0xf bank_mask:0xf bound_ctrl:1
	v_pk_fma_f32 v[142:143], v[18:19], v[54:55], v[142:143]
	v_pk_fma_f32 v[144:145], v[18:19], v[38:39], v[144:145]
	v_cndmask_b32_e64 v28, v28, v216, s[36:37]
	v_pk_fma_f32 v[16:17], v[68:69], v[148:149], v[140:141] op_sel:[0,1,0] op_sel_hi:[1,1,1]
	v_pk_fma_f32 v[18:19], v[70:71], v[148:149], v[142:143] op_sel:[0,1,0] op_sel_hi:[1,1,1]
	v_pk_mul_f32 v[146:147], v[16:17], v[56:57]
	v_pk_fma_f32 v[146:147], v[18:19], v[58:59], v[146:147]
	s_waitcnt lgkmcnt(6)
	v_pk_mul_f32 v[132:133], v[16:17], v[84:85]
	v_pk_mul_f32 v[134:135], v[16:17], v[104:105]
	v_add_f32_e32 v200, v144, v145
	v_pk_fma_f32 v[132:133], v[18:19], v[86:87], v[132:133]
	v_pk_fma_f32 v[134:135], v[18:19], v[106:107], v[134:135]
	v_add_f32_e32 v201, v146, v147
	v_pk_mul_f32 v[136:137], v[114:115], v[80:81] op_sel_hi:[0,1]
	v_add_f32_e32 v148, v132, v133
	v_add_f32_e32 v149, v134, v135
	v_pk_mul_f32 v[138:139], v[114:115], v[82:83] op_sel_hi:[0,1]
	v_add_f32_dpp v148, v148, v148 quad_perm:[1,0,3,2] row_mask:0xf bank_mask:0xf bound_ctrl:1
	v_add_f32_dpp v149, v149, v149 quad_perm:[1,0,3,2] row_mask:0xf bank_mask:0xf bound_ctrl:1
	v_pk_fma_f32 v[136:137], v[16:17], v[72:73], v[136:137]
	v_add_f32_dpp v148, v148, v148 quad_perm:[2,3,0,1] row_mask:0xf bank_mask:0xf bound_ctrl:1
	v_add_f32_dpp v149, v149, v149 quad_perm:[2,3,0,1] row_mask:0xf bank_mask:0xf bound_ctrl:1
	v_pk_fma_f32 v[138:139], v[18:19], v[74:75], v[138:139]
	v_add_f32_dpp v148, v148, v148 row_half_mirror row_mask:0xf bank_mask:0xf bound_ctrl:1
	v_add_f32_dpp v149, v149, v149 row_half_mirror row_mask:0xf bank_mask:0xf bound_ctrl:1
	ds_read_b128 v[172:175], v29 offset:35888
	ds_read_b128 v[192:195], v29 offset:37168
	ds_read_b128 v[168:171], v29 offset:35872
	ds_read_b128 v[116:119], v31 offset:112
	ds_read_b128 v[160:163], v29 offset:35840
	ds_read_b128 v[176:179], v29 offset:35904
	ds_read_b128 v[188:191], v29 offset:37152
	ds_read_b128 v[180:183], v29 offset:37120
	ds_read_b128 v[164:167], v29 offset:35856
	ds_read_b128 v[196:199], v29 offset:37184
	ds_read_b128 v[184:187], v29 offset:37136
	s_waitcnt lgkmcnt(11)
	v_pk_mul_f32 v[140:141], v[114:115], v[100:101] op_sel:[1,0] op_sel_hi:[1,1]
	v_add_f32_dpp v148, v148, v148 row_mirror row_mask:0xf bank_mask:0xf bound_ctrl:1
	v_add_f32_dpp v149, v149, v149 row_mirror row_mask:0xf bank_mask:0xf bound_ctrl:1
	v_pk_mul_f32 v[142:143], v[114:115], v[102:103] op_sel:[1,0] op_sel_hi:[1,1]
	v_fmac_f32_e32 v149, v114, v125
	v_pk_fma_f32 v[16:17], v[88:89], v[148:149], v[136:137] op_sel_hi:[1,0,1]
	v_pk_fma_f32 v[18:19], v[90:91], v[148:149], v[138:139] op_sel_hi:[1,0,1]
	v_pk_fma_f32 v[140:141], v[16:17], v[92:93], v[140:141]
	v_pk_mul_f32 v[144:145], v[16:17], v[76:77]
	v_pk_fma_f32 v[142:143], v[18:19], v[94:95], v[142:143]
	v_pk_fma_f32 v[144:145], v[18:19], v[78:79], v[144:145]
	v_pk_fma_f32 v[16:17], v[108:109], v[148:149], v[140:141] op_sel:[0,1,0] op_sel_hi:[1,1,1]
	v_pk_fma_f32 v[18:19], v[110:111], v[148:149], v[142:143] op_sel:[0,1,0] op_sel_hi:[1,1,1]
	v_pk_mul_f32 v[146:147], v[16:17], v[96:97]
	v_pk_fma_f32 v[146:147], v[18:19], v[98:99], v[146:147]
	s_waitcnt lgkmcnt(6)
	v_pk_mul_f32 v[132:133], v[16:17], v[172:173]
	v_pk_mul_f32 v[134:135], v[16:17], v[192:193]
	v_add_f32_e32 v202, v144, v145
	v_pk_fma_f32 v[132:133], v[18:19], v[174:175], v[132:133]
	v_pk_fma_f32 v[134:135], v[18:19], v[194:195], v[134:135]
	v_add_f32_e32 v203, v146, v147
	v_pk_mul_f32 v[136:137], v[116:117], v[168:169] op_sel_hi:[0,1]
	v_add_f32_e32 v148, v132, v133
	v_cndmask_b32_e64 v208, v200, v201, s[10:11]
	v_add_f32_e32 v149, v134, v135
	v_pk_mul_f32 v[138:139], v[116:117], v[170:171] op_sel_hi:[0,1]
	v_cndmask_b32_e64 v209, v201, v200, s[10:11]
	v_add_f32_dpp v148, v148, v148 quad_perm:[1,0,3,2] row_mask:0xf bank_mask:0xf bound_ctrl:1
	v_add_f32_dpp v149, v149, v149 quad_perm:[1,0,3,2] row_mask:0xf bank_mask:0xf bound_ctrl:1
	v_cndmask_b32_e64 v210, v202, v203, s[10:11]
	v_pk_fma_f32 v[136:137], v[16:17], v[160:161], v[136:137]
	v_add_f32_dpp v148, v148, v148 quad_perm:[2,3,0,1] row_mask:0xf bank_mask:0xf bound_ctrl:1
	v_cndmask_b32_e64 v211, v203, v202, s[10:11]
	v_add_f32_dpp v149, v149, v149 quad_perm:[2,3,0,1] row_mask:0xf bank_mask:0xf bound_ctrl:1
	v_pk_fma_f32 v[138:139], v[18:19], v[162:163], v[138:139]
	v_add_f32_dpp v212, v209, v208 quad_perm:[1,0,3,2] row_mask:0xf bank_mask:0xf bound_ctrl:1
	v_add_f32_dpp v148, v148, v148 row_half_mirror row_mask:0xf bank_mask:0xf bound_ctrl:1
	v_add_f32_dpp v149, v149, v149 row_half_mirror row_mask:0xf bank_mask:0xf bound_ctrl:1
	v_add_f32_dpp v213, v211, v210 quad_perm:[1,0,3,2] row_mask:0xf bank_mask:0xf bound_ctrl:1
	ds_read_b128 v[44:47], v29 offset:38448
	ds_read_b128 v[64:67], v29 offset:39728
	ds_read_b128 v[40:43], v29 offset:38432
	ds_read_b128 v[32:35], v29 offset:38400
	ds_read_b128 v[48:51], v29 offset:38464
	ds_read_b128 v[60:63], v29 offset:39712
	ds_read_b128 v[52:55], v29 offset:39680
	ds_read_b128 v[36:39], v29 offset:38416
	ds_read_b128 v[68:71], v29 offset:39744
	ds_read_b128 v[56:59], v29 offset:39696
	s_waitcnt lgkmcnt(10)
	v_pk_mul_f32 v[140:141], v[116:117], v[188:189] op_sel:[1,0] op_sel_hi:[1,1]
	v_cndmask_b32_e64 v214, v212, v213, s[14:15]
	v_add_f32_dpp v148, v148, v148 row_mirror row_mask:0xf bank_mask:0xf bound_ctrl:1
	v_add_f32_dpp v149, v149, v149 row_mirror row_mask:0xf bank_mask:0xf bound_ctrl:1
	v_cndmask_b32_e64 v215, v213, v212, s[14:15]
	v_pk_mul_f32 v[142:143], v[116:117], v[190:191] op_sel:[1,0] op_sel_hi:[1,1]
	v_fmac_f32_e32 v149, v116, v126
	v_add_f32_dpp v216, v215, v214 quad_perm:[2,3,0,1] row_mask:0xf bank_mask:0xf bound_ctrl:1
	v_pk_fma_f32 v[16:17], v[176:177], v[148:149], v[136:137] op_sel_hi:[1,0,1]
	v_pk_fma_f32 v[18:19], v[178:179], v[148:149], v[138:139] op_sel_hi:[1,0,1]
	v_add_f32_dpp v216, v216, v216 row_ror:8 row_mask:0xf bank_mask:0xf bound_ctrl:1
	v_pk_fma_f32 v[140:141], v[16:17], v[180:181], v[140:141]
	v_pk_mul_f32 v[144:145], v[16:17], v[164:165]
	v_add_f32_dpp v216, v216, v216 row_ror:4 row_mask:0xf bank_mask:0xf bound_ctrl:1
	v_pk_fma_f32 v[142:143], v[18:19], v[182:183], v[142:143]
	v_pk_fma_f32 v[144:145], v[18:19], v[166:167], v[144:145]
	v_cndmask_b32_e64 v28, v28, v216, s[42:43]
	v_pk_fma_f32 v[16:17], v[196:197], v[148:149], v[140:141] op_sel:[0,1,0] op_sel_hi:[1,1,1]
	v_pk_fma_f32 v[18:19], v[198:199], v[148:149], v[142:143] op_sel:[0,1,0] op_sel_hi:[1,1,1]
	v_pk_mul_f32 v[146:147], v[16:17], v[184:185]
	v_pk_fma_f32 v[146:147], v[18:19], v[186:187], v[146:147]
	s_waitcnt lgkmcnt(6)
	v_pk_mul_f32 v[132:133], v[16:17], v[44:45]
	v_pk_mul_f32 v[134:135], v[16:17], v[64:65]
	v_add_f32_e32 v204, v144, v145
	v_pk_fma_f32 v[132:133], v[18:19], v[46:47], v[132:133]
	v_pk_fma_f32 v[134:135], v[18:19], v[66:67], v[134:135]
	v_add_f32_e32 v205, v146, v147
	v_pk_mul_f32 v[136:137], v[118:119], v[40:41] op_sel_hi:[0,1]
	v_add_f32_e32 v148, v132, v133
	v_add_f32_e32 v149, v134, v135
	v_pk_mul_f32 v[138:139], v[118:119], v[42:43] op_sel_hi:[0,1]
	v_add_f32_dpp v148, v148, v148 quad_perm:[1,0,3,2] row_mask:0xf bank_mask:0xf bound_ctrl:1
	v_add_f32_dpp v149, v149, v149 quad_perm:[1,0,3,2] row_mask:0xf bank_mask:0xf bound_ctrl:1
	v_pk_fma_f32 v[136:137], v[16:17], v[32:33], v[136:137]
	v_add_f32_dpp v148, v148, v148 quad_perm:[2,3,0,1] row_mask:0xf bank_mask:0xf bound_ctrl:1
	v_add_f32_dpp v149, v149, v149 quad_perm:[2,3,0,1] row_mask:0xf bank_mask:0xf bound_ctrl:1
	v_pk_fma_f32 v[138:139], v[18:19], v[34:35], v[138:139]
	v_add_f32_dpp v148, v148, v148 row_half_mirror row_mask:0xf bank_mask:0xf bound_ctrl:1
	v_add_f32_dpp v149, v149, v149 row_half_mirror row_mask:0xf bank_mask:0xf bound_ctrl:1
	s_waitcnt lgkmcnt(0)
	v_pk_mul_f32 v[140:141], v[118:119], v[60:61] op_sel:[1,0] op_sel_hi:[1,1]
	v_add_f32_dpp v148, v148, v148 row_mirror row_mask:0xf bank_mask:0xf bound_ctrl:1
	v_add_f32_dpp v149, v149, v149 row_mirror row_mask:0xf bank_mask:0xf bound_ctrl:1
	v_pk_mul_f32 v[142:143], v[118:119], v[62:63] op_sel:[1,0] op_sel_hi:[1,1]
	v_fmac_f32_e32 v149, v118, v127
	v_pk_fma_f32 v[16:17], v[48:49], v[148:149], v[136:137] op_sel_hi:[1,0,1]
	v_pk_fma_f32 v[18:19], v[50:51], v[148:149], v[138:139] op_sel_hi:[1,0,1]
	v_pk_fma_f32 v[140:141], v[16:17], v[52:53], v[140:141]
	v_pk_mul_f32 v[144:145], v[16:17], v[36:37]
	v_pk_fma_f32 v[142:143], v[18:19], v[54:55], v[142:143]
	v_pk_fma_f32 v[144:145], v[18:19], v[38:39], v[144:145]
	v_pk_fma_f32 v[16:17], v[68:69], v[148:149], v[140:141] op_sel:[0,1,0] op_sel_hi:[1,1,1]
	v_pk_fma_f32 v[18:19], v[70:71], v[148:149], v[142:143] op_sel:[0,1,0] op_sel_hi:[1,1,1]
	v_pk_mul_f32 v[146:147], v[16:17], v[56:57]
	v_pk_fma_f32 v[146:147], v[18:19], v[58:59], v[146:147]
	s_mov_b64 exec, 1
	ds_add_u32 v221, v222
	s_mov_b64 exec, -1
	ds_read_b128 v[224:227], v220
.LBB0_498:
	s_andn2_saveexec_b64 s[52:53], s[52:53]
	s_cbranch_execz .LBB0_495
	s_cmpk_eq_i32 s58, 0x7f
	s_cbranch_scc1 .LBB0_495
	v_lshl_add_u64 v[14:15], v[8:9], 0, s[28:29]
	global_load_dwordx4 v[30:33], v[14:15], off
	v_lshl_add_u64 v[14:15], v[10:11], 0, s[28:29]
	v_add_co_u32_e32 v34, vcc, 0xd504000, v14
	v_lshl_add_u64 v[38:39], v[6:7], 0, s[28:29]
	s_nop 0
	v_addc_co_u32_e32 v35, vcc, 0, v15, vcc
	global_load_dwordx2 v[44:45], v[34:35], off
	v_add_co_u32_e32 v34, vcc, s60, v38
	s_xor_b32 s11, s54, 1
	s_nop 0
	v_addc_co_u32_e32 v35, vcc, 0, v39, vcc
	global_load_dwordx2 v[40:41], v[34:35], off
	v_add_co_u32_e32 v34, vcc, s61, v38
	s_mul_i32 s15, s11, 0xa000
	s_nop 0
	v_addc_co_u32_e32 v35, vcc, 0, v39, vcc
	global_load_dwordx2 v[46:47], v[34:35], off
	v_add_co_u32_e32 v34, vcc, 0xdd04000, v14
	s_add_i32 s15, s15, 0
	s_nop 0
	v_addc_co_u32_e32 v35, vcc, 0, v15, vcc
	global_load_dwordx2 v[48:49], v[34:35], off
	v_add_co_u32_e32 v34, vcc, 0xe504000, v14
	v_add_u32_e32 v29, s15, v21
	s_nop 0
	v_addc_co_u32_e32 v35, vcc, 0, v15, vcc
	v_add_co_u32_e32 v14, vcc, 0xed04000, v14
	global_load_dwordx2 v[50:51], v[34:35], off
	s_nop 0
	v_addc_co_u32_e32 v15, vcc, 0, v15, vcc
	v_add_co_u32_e32 v42, vcc, s62, v38
	global_load_dwordx2 v[14:15], v[14:15], off
	s_nop 0
	v_addc_co_u32_e32 v43, vcc, 0, v39, vcc
	v_add_co_u32_e32 v38, vcc, s63, v38
	v_lshl_add_u64 v[34:35], v[4:5], 0, s[28:29]
	global_load_dwordx2 v[52:53], v[42:43], off
	v_addc_co_u32_e32 v39, vcc, 0, v39, vcc
	global_load_dwordx4 v[34:37], v[34:35], off
	s_mulk_i32 s11, 0xa00
	global_load_dwordx2 v[54:55], v[38:39], off
	s_add_i32 s11, s11, 0
	v_add_u32_e32 v56, s15, v20
	s_add_i32 s11, s11, 0x14000
	v_mov_b32_e32 v57, 0x1f010
	s_movk_i32 s33, 0x4000
.Lld_poll0:
	ds_read_b128 v[60:63], v57
	s_waitcnt lgkmcnt(0)
	v_min3_u32 v58, v60, v61, v62
	v_min_u32_e32 v58, v58, v63
	s_nop 0
	v_readfirstlane_b32 s41, v58
	s_cmp_ge_u32 s41, s58
	s_cbranch_scc1 .Lld_ok0
	s_sub_u32 s33, s33, 1
	s_cmp_eq_u32 s33, 0
	s_cbranch_scc1 .Lld_ok0
	s_sleep 1
	s_branch .Lld_poll0
.Lld_ok0:
	s_waitcnt vmcnt(9)
	ds_write_b128 v29, v[30:33]
	s_waitcnt vmcnt(8)
	v_lshlrev_b32_e32 v42, 16, v44
	v_and_b32_e32 v43, 0xffff0000, v44
	v_lshlrev_b32_e32 v44, 16, v45
	v_and_b32_e32 v45, 0xffff0000, v45
	ds_write_b128 v29, v[42:45] offset:16
	s_waitcnt vmcnt(7)
	v_lshlrev_b32_e32 v30, 16, v40
	v_and_b32_e32 v31, 0xffff0000, v40
	v_lshlrev_b32_e32 v32, 16, v41
	v_and_b32_e32 v33, 0xffff0000, v41
	s_waitcnt vmcnt(6)
	v_lshlrev_b32_e32 v38, 16, v46
	v_and_b32_e32 v39, 0xffff0000, v46
	v_lshlrev_b32_e32 v40, 16, v47
	v_and_b32_e32 v41, 0xffff0000, v47
	s_waitcnt vmcnt(5)
	v_lshlrev_b32_e32 v42, 16, v48
	v_and_b32_e32 v43, 0xffff0000, v48
	v_lshlrev_b32_e32 v44, 16, v49
	v_and_b32_e32 v45, 0xffff0000, v49
	ds_write_b128 v29, v[42:45] offset:32
	s_waitcnt vmcnt(4)
	v_lshlrev_b32_e32 v42, 16, v50
	v_and_b32_e32 v43, 0xffff0000, v50
	v_lshlrev_b32_e32 v44, 16, v51
	v_and_b32_e32 v45, 0xffff0000, v51
	ds_write_b128 v29, v[42:45] offset:48
	s_waitcnt vmcnt(3)
	v_lshlrev_b32_e32 v42, 16, v14
	v_and_b32_e32 v43, 0xffff0000, v14
	v_lshlrev_b32_e32 v44, 16, v15
	v_and_b32_e32 v45, 0xffff0000, v15
	ds_write_b128 v29, v[42:45] offset:64
	s_waitcnt vmcnt(1)
	ds_write_b128 v56, v[34:37]
	ds_write_b128 v56, v[30:33] offset:16
	v_lshlrev_b32_e32 v30, 16, v52
	v_and_b32_e32 v31, 0xffff0000, v52
	v_lshlrev_b32_e32 v32, 16, v53
	v_and_b32_e32 v33, 0xffff0000, v53
	ds_write_b128 v56, v[30:33] offset:48
	s_waitcnt vmcnt(0)
	v_lshlrev_b32_e32 v30, 16, v54
	v_and_b32_e32 v31, 0xffff0000, v54
	v_lshlrev_b32_e32 v32, 16, v55
	v_and_b32_e32 v33, 0xffff0000, v55
	ds_write_b128 v56, v[38:41] offset:32
	ds_write_b128 v56, v[30:33] offset:64
	s_and_saveexec_b64 s[40:41], s[6:7]
	s_xor_b64 s[54:55], exec, s[40:41]
	s_cbranch_execz .LBB0_504
	s_and_saveexec_b64 s[56:57], s[8:9]
	s_cbranch_execz .LBB0_503
	v_lshl_add_u64 v[14:15], v[2:3], 0, s[28:29]
	global_load_dword v14, v[14:15], off
	v_add_u32_e32 v15, s11, v25
	s_waitcnt vmcnt(0)
	ds_write_b32 v15, v14 offset:64
